# grid barrier: XCD leaders also arrive on a second copy of the cross-XCD counter and the non-leader workgroups poll that copy, keeping the polling off the line the arrival atomics use
# baseline (speedup 1.0000x reference)
.LBB0_683:
	s_or_b64 exec, exec, s[0:1]
	v_cvt_f32_u32_e32 v4, v2
	s_waitcnt vmcnt(0)
	v_readfirstlane_b32 s0, v3
	v_sub_u32_e32 v3, 0, v2
	v_rcp_iflag_f32_e32 v4, v4
	v_add_u32_e32 v5, s0, v1
	v_mul_f32_e32 v4, 0x4f7ffffe, v4
	v_cvt_u32_f32_e32 v4, v4
	v_mul_lo_u32 v1, v3, v4
	v_mul_hi_u32 v1, v4, v1
	v_add_u32_e32 v1, v4, v1
	v_mul_hi_u32 v1, v5, v1
	v_mul_lo_u32 v3, v1, v2
	v_sub_u32_e32 v3, v5, v3
	v_add_u32_e32 v4, 1, v1
	v_cmp_ge_u32_e32 vcc, v3, v2
	s_nop 1
	v_cndmask_b32_e32 v1, v1, v4, vcc
	v_sub_u32_e32 v4, v3, v2
	v_cndmask_b32_e32 v3, v3, v4, vcc
	v_add_u32_e32 v4, 1, v1
	v_cmp_ge_u32_e32 vcc, v3, v2
	v_add_u32_e32 v3, 1, v5
	s_nop 0
	v_cndmask_b32_e32 v1, v1, v4, vcc
	v_mul_lo_u32 v4, v2, v1
	v_add_u32_e32 v2, v4, v2
	v_cmp_ne_u32_e32 vcc, v3, v2
	s_and_saveexec_b64 s[0:1], vcc
	s_xor_b64 s[0:1], exec, s[0:1]
	s_cbranch_execz .LBB0_697
	v_readlane_b32 s4, v254, 11
	v_readlane_b32 s5, v254, 12
	s_sub_u32 s4, s4, 0x3400
	s_subb_u32 s5, s5, 0
	s_waitcnt lgkmcnt(0)
	v_mad_u32_u24 v1, v1, v0, v0
	s_nop 3
	global_load_dword v0, v113, s[4:5] sc1
	s_waitcnt vmcnt(0)
	v_cmp_lt_u32_e32 vcc, v0, v1
	s_and_saveexec_b64 s[4:5], vcc
	s_cbranch_execz .LBB0_696
	s_mov_b32 s18, 1
	s_mov_b64 s[6:7], 0
	s_branch .LBB0_687

.LBB0_689:
	v_readlane_b32 s10, v254, 11
	v_readlane_b32 s11, v254, 12
	s_sub_u32 s10, s10, 0x3400
	s_subb_u32 s11, s11, 0
	s_add_i32 s18, s18, 1
	s_mov_b64 s[12:13], -1
	s_nop 2
	global_load_dword v0, v113, s[10:11] sc1
	s_waitcnt vmcnt(0)
	v_cmp_ge_u32_e32 vcc, v0, v1
	s_orn2_b64 s[10:11], vcc, exec
	s_branch .LBB0_686

.LBB0_697:
	s_andn2_saveexec_b64 s[0:1], s[0:1]
	s_cbranch_execz .LBB0_21
	s_mov_b64 s[0:1], exec
	buffer_wbl2 sc1
	s_waitcnt lgkmcnt(0)
	s_waitcnt vmcnt(0)
	v_mbcnt_lo_u32_b32 v1, s0, 0
	v_mbcnt_hi_u32_b32 v1, s1, v1
	v_cmp_eq_u32_e32 vcc, 0, v1
	s_and_saveexec_b64 s[4:5], vcc
	s_cbranch_execz .LBB0_700
	s_bcnt1_i32_b64 s0, s[0:1]
	v_mov_b32_e32 v2, s0
	v_readlane_b32 s0, v254, 11
	v_readlane_b32 s1, v254, 12
	s_sub_u32 s6, s0, 0x3400
	s_subb_u32 s7, s1, 0
	s_nop 2
	global_atomic_add v113, v2, s[6:7]
	global_atomic_add v2, v113, v2, s[0:1] sc0
